# phase-0 weight transposes without gains (W2, PLE gate/up, even out): two tiles of global loads in flight (second register set, counted vmcnt)
# speedup vs baseline: 1.0010x; 1.0010x over previous
.LBB0_843:
	v_mov_b32_e32 v10, v142
	s_mov_b32 s1, s88
	s_waitcnt lgkmcnt(0)
	s_barrier
	s_addk_i32 s1, 0xfa00
	s_ashr_i32 s4, s1, 31
	s_abs_i32 s1, s1
	v_readlane_b32 s6, v254, 22
	s_mul_hi_u32 s5, s1, s6
	s_mul_i32 s5, s5, s77
	s_sub_i32 s1, s1, s5
	s_sub_i32 s5, s1, s77
	s_cmp_ge_u32 s1, s77
	s_cselect_b32 s1, s5, s1
	s_sub_i32 s5, s1, s77
	s_cmp_ge_u32 s1, s77
	s_cselect_b32 s1, s5, s1
	s_xor_b32 s1, s1, s4
	s_sub_i32 s1, s1, s4
	s_add_i32 s1, s1, s46
	s_ashr_i32 s4, s1, 31
	s_abs_i32 s1, s1
	s_mul_hi_u32 s5, s1, s6
	s_mul_i32 s5, s5, s77
	s_sub_i32 s1, s1, s5
	s_sub_i32 s5, s1, s77
	s_cmp_ge_u32 s1, s77
	s_cselect_b32 s1, s5, s1
	s_sub_i32 s5, s1, s77
	s_cmp_ge_u32 s1, s77
	s_cselect_b32 s1, s5, s1
	s_xor_b32 s1, s1, s4
	s_sub_i32 s10, s1, s4
	s_cmpk_gt_i32 s10, 0x1ff
	s_cbranch_scc1 .LBB0_856
	v_readlane_b32 s4, v254, 60
	v_readlane_b32 s5, v254, 61
	s_add_u32 s1, s50, 0xc00000
	s_load_dwordx2 s[6:7], s[4:5], 0xb8
	s_addc_u32 s4, s51, 0
	s_ashr_i32 s5, s10, 31
	s_lshr_b32 s5, s5, 24
	s_add_i32 s5, s10, s5
	s_ashr_i32 s8, s5, 8
	s_and_b32 s5, s5, 0xff00
	s_sub_i32 s5, s10, s5
	s_sext_i32_i16 s9, s5
	s_bfe_u32 s9, s9, 0x4001b
	s_add_i32 s9, s5, s9
	s_sext_i32_i16 s11, s9
	s_and_b32 s9, s9, 0xfff0
	s_sub_i32 s5, s5, s9
	s_lshl_b32 s11, s11, 2
	s_sext_i32_i16 s5, s5
	s_ashr_i32 s9, s8, 31
	s_andn2_b32 s11, s11, 63
	s_waitcnt lgkmcnt(0)
	s_lshl_b32 s12, s5, 6
	s_lshl_b64 s[8:9], s[8:9], 22
	s_add_u32 s5, s6, s8
	s_addc_u32 s14, s7, s9
	s_ashr_i32 s13, s12, 31
	v_add_u32_e32 v11, 0x200, v10
	v_lshlrev_b32_e32 v0, 2, v10
	s_lshl_b64 s[8:9], s[12:13], 2
	v_ashrrev_i32_e32 v14, 4, v10
	v_ashrrev_i32_e32 v15, 4, v11
	v_and_b32_e32 v12, 60, v0
	s_add_u32 s8, s5, s8
	s_waitcnt vmcnt(0)
	v_add_u32_e32 v4, s11, v14
	v_add_u32_e32 v6, s11, v15
	s_addc_u32 s9, s14, s9
	v_lshlrev_b32_e32 v0, 2, v12
	v_ashrrev_i32_e32 v5, 31, v4
	v_ashrrev_i32_e32 v7, 31, v6
	v_lshl_add_u64 v[2:3], s[8:9], 0, v[0:1]
	v_lshlrev_b64 v[4:5], 12, v[4:5]
	v_lshlrev_b64 v[6:7], 12, v[6:7]
	v_lshl_add_u64 v[4:5], v[2:3], 0, v[4:5]
	v_lshl_add_u64 v[6:7], v[2:3], 0, v[6:7]
	global_load_dwordx4 v[2:5], v[4:5], off
	s_nop 0
	global_load_dwordx4 v[6:9], v[6:7], off
	v_lshlrev_b32_e32 v13, 1, v10
	v_and_b32_e32 v26, 62, v13
	s_movk_i32 s5, 0x104
	v_mul_u32_u24_e32 v13, 0x41, v26
	v_mul_lo_u32 v16, v14, s5
	v_mul_lo_u32 v17, v15, s5
	v_ashrrev_i32_e32 v18, 5, v10
	v_ashrrev_i32_e32 v20, 5, v11
	v_add_u32_e32 v11, 0x400, v10
	v_add_u32_e32 v10, 0x600, v10
	v_add3_u32 v16, s89, v16, v0
	v_add3_u32 v17, s89, v17, v0
	v_lshl_add_u32 v0, v13, 2, s89
	v_ashrrev_i32_e32 v22, 5, v11
	v_ashrrev_i32_e32 v24, 5, v10
	v_lshl_add_u32 v19, v18, 2, v0
	v_lshl_add_u32 v21, v20, 2, v0
	v_lshl_add_u32 v23, v22, 2, v0
	v_lshl_add_u32 v25, v24, 2, v0
	v_lshlrev_b32_e32 v10, 2, v12
	v_lshlrev_b32_e32 v0, 1, v26
	s_mov_b32 s98, 1
	s_mov_b32 s99, 2
	s_sub_i32 s10, s10, s46
	s_branch .LBB0_846

.Ltq1_latch2:
	s_xor_b32 s98, s98, 1
	s_sub_i32 s99, s99, 1
	s_max_i32 s99, s99, 0
	s_andn2_b64 vcc, exec, s[8:9]
	s_mov_b32 s10, s5
	s_cbranch_vccz .LBB0_856
.LBB0_846:
	s_cmp_eq_u32 s99, 2
	s_cbranch_scc0 .Ltq1_real
	s_add_i32 s5, s10, s46
	s_mov_b64 s[8:9], 0
	s_branch .Ltq1_fchk
.Ltq1_real:
	s_waitcnt lgkmcnt(0)
	s_barrier
	s_add_i32 s5, s10, s46
	s_cmpk_gt_i32 s5, 0x1ff
	s_cbranch_scc1 .Ltq1_w0
	s_cmp_eq_u32 s99, 1
	s_cbranch_scc1 .Ltq1_w2
	s_waitcnt vmcnt(6)
	s_branch .Ltq1_wd
.Ltq1_w2:
	s_waitcnt vmcnt(2)
	s_branch .Ltq1_wd

.Ltq1_wd:
	s_cmp_eq_u32 s98, 0
	s_cbranch_scc0 .Ltq1_wrB
	ds_write2_b32 v16, v2, v3 offset1:1
	ds_write2_b32 v16, v4, v5 offset0:2 offset1:3
	ds_write2_b32 v17, v6, v7 offset1:1
	ds_write2_b32 v17, v8, v9 offset0:2 offset1:3
	s_branch .Ltq1_wrd
.Ltq1_wrB:
	ds_write2_b32 v16, v100, v101 offset1:1
	ds_write2_b32 v16, v102, v103 offset0:2 offset1:3
	ds_write2_b32 v17, v104, v105 offset1:1
	ds_write2_b32 v17, v106, v107 offset0:2 offset1:3
.Ltq1_wrd:
	s_waitcnt lgkmcnt(0)
	s_barrier
	s_cmpk_gt_i32 s5, 0x1ff
	s_cselect_b64 s[8:9], -1, 0
.Ltq1_fchk:
	s_add_i32 s100, s5, s46
	s_cmpk_gt_i32 s100, 0x1ff
	s_cbranch_scc1 .Ltq1_nof
	s_cmp_eq_u32 s98, 0
	s_cbranch_scc0 .Ltq1_fB
	s_ashr_i32 s11, s100, 31
	s_lshr_b32 s11, s11, 24
	s_add_i32 s11, s100, s11
	s_ashr_i32 s12, s11, 8
	s_and_b32 s11, s11, 0xff00
	s_sub_i32 s11, s100, s11
	s_sext_i32_i16 s13, s11
	s_bfe_u32 s13, s13, 0x4001b
	s_add_i32 s13, s11, s13
	s_sext_i32_i16 s14, s13
	s_and_b32 s13, s13, 0xfff0
	s_sub_i32 s11, s11, s13
	s_lshl_b32 s14, s14, 2
	s_sext_i32_i16 s11, s11
	s_ashr_i32 s13, s12, 31
	s_and_b32 s16, s14, 0xffffffc0
	s_lshl_b32 s14, s11, 6
	s_lshl_b64 s[12:13], s[12:13], 22
	s_add_u32 s11, s6, s12
	s_addc_u32 s17, s7, s13
	s_ashr_i32 s15, s14, 31
	s_lshl_b64 s[12:13], s[14:15], 2
	s_add_u32 s12, s11, s12
	v_add_u32_e32 v4, s16, v14
	v_add_u32_e32 v6, s16, v15
	s_addc_u32 s13, s17, s13
	v_mov_b32_e32 v11, v1
	v_ashrrev_i32_e32 v5, 31, v4
	v_ashrrev_i32_e32 v7, 31, v6
	v_lshl_add_u64 v[2:3], s[12:13], 0, v[10:11]
	v_lshlrev_b64 v[4:5], 12, v[4:5]
	v_lshlrev_b64 v[6:7], 12, v[6:7]
	v_lshl_add_u64 v[4:5], v[2:3], 0, v[4:5]
	v_lshl_add_u64 v[6:7], v[2:3], 0, v[6:7]
	global_load_dwordx4 v[2:5], v[4:5], off
	s_nop 0
	global_load_dwordx4 v[6:9], v[6:7], off
	s_branch .Ltq1_nof
.Ltq1_fB:
	s_ashr_i32 s11, s100, 31
	s_lshr_b32 s11, s11, 24
	s_add_i32 s11, s100, s11
	s_ashr_i32 s12, s11, 8
	s_and_b32 s11, s11, 0xff00
	s_sub_i32 s11, s100, s11
	s_sext_i32_i16 s13, s11
	s_bfe_u32 s13, s13, 0x4001b
	s_add_i32 s13, s11, s13
	s_sext_i32_i16 s14, s13
	s_and_b32 s13, s13, 0xfff0
	s_sub_i32 s11, s11, s13
	s_lshl_b32 s14, s14, 2
	s_sext_i32_i16 s11, s11
	s_ashr_i32 s13, s12, 31
	s_and_b32 s16, s14, 0xffffffc0
	s_lshl_b32 s14, s11, 6
	s_lshl_b64 s[12:13], s[12:13], 22
	s_add_u32 s11, s6, s12
	s_addc_u32 s17, s7, s13
	s_ashr_i32 s15, s14, 31
	s_lshl_b64 s[12:13], s[14:15], 2
	s_add_u32 s12, s11, s12
	v_add_u32_e32 v102, s16, v14
	v_add_u32_e32 v104, s16, v15
	s_addc_u32 s13, s17, s13
	v_mov_b32_e32 v11, v1
	v_ashrrev_i32_e32 v103, 31, v102
	v_ashrrev_i32_e32 v105, 31, v104
	v_lshl_add_u64 v[100:101], s[12:13], 0, v[10:11]
	v_lshlrev_b64 v[102:103], 12, v[102:103]
	v_lshlrev_b64 v[104:105], 12, v[104:105]
	v_lshl_add_u64 v[102:103], v[100:101], 0, v[102:103]
	v_lshl_add_u64 v[104:105], v[100:101], 0, v[104:105]
	global_load_dwordx4 v[100:103], v[102:103], off
	s_nop 0
	global_load_dwordx4 v[104:107], v[104:105], off
.Ltq1_nof:
	s_cmp_eq_u32 s99, 2
	s_cbranch_scc1 .Ltq1_latch2

.LBB0_964:
	v_mov_b32_e32 v10, v142
	s_mov_b32 s1, s88
	s_waitcnt lgkmcnt(0)
	s_barrier
	s_addk_i32 s1, 0xd3e0
	s_waitcnt lgkmcnt(0)
	s_ashr_i32 s2, s1, 31
	s_abs_i32 s1, s1
	v_readlane_b32 s4, v254, 22
	s_mul_hi_u32 s3, s1, s4
	s_mul_i32 s3, s3, s77
	s_sub_i32 s1, s1, s3
	s_sub_i32 s3, s1, s77
	s_cmp_ge_u32 s1, s77
	s_cselect_b32 s1, s3, s1
	s_sub_i32 s3, s1, s77
	s_cmp_ge_u32 s1, s77
	s_cselect_b32 s1, s3, s1
	s_xor_b32 s1, s1, s2
	s_sub_i32 s1, s1, s2
	s_add_i32 s1, s1, s46
	s_ashr_i32 s2, s1, 31
	s_abs_i32 s1, s1
	s_mul_hi_u32 s3, s1, s4
	s_mul_i32 s3, s3, s77
	s_sub_i32 s1, s1, s3
	s_sub_i32 s3, s1, s77
	s_cmp_ge_u32 s1, s77
	s_cselect_b32 s1, s3, s1
	s_sub_i32 s3, s1, s77
	s_cmp_ge_u32 s1, s77
	s_cselect_b32 s1, s3, s1
	s_xor_b32 s1, s1, s2
	s_sub_i32 s8, s1, s2
	s_cmpk_gt_i32 s8, 0xaff
	s_cbranch_scc1 .LBB0_977
	s_add_u32 s1, s50, 0x5900000
	s_mul_hi_i32 s5, s8, 0x2e8ba2e9
	s_addc_u32 s4, s51, 0
	s_lshr_b32 s6, s5, 31
	s_ashr_i32 s5, s5, 7
	s_add_i32 s5, s5, s6
	s_mul_i32 s6, s5, 0x2c0
	v_readlane_b32 s2, v254, 60
	s_sub_i32 s6, s8, s6
	v_readlane_b32 s3, v254, 61
	s_bfe_u32 s7, s6, 0x4001b
	s_load_dwordx2 s[2:3], s[2:3], 0x110
	s_add_i32 s7, s6, s7
	s_sext_i32_i16 s9, s7
	s_and_b32 s7, s7, 0xfff0
	s_sub_i32 s6, s6, s7
	s_lshl_b32 s9, s9, 2
	s_sext_i32_i16 s6, s6
	s_andn2_b32 s9, s9, 63
	s_lshl_b32 s6, s6, 6
	s_mul_hi_i32 s7, s5, 0xb00000
	s_mul_i32 s5, s5, 0xb00000
	s_waitcnt lgkmcnt(0)
	s_add_u32 s5, s2, s5
	s_addc_u32 s10, s3, s7
	s_ashr_i32 s7, s6, 31
	v_add_u32_e32 v11, 0x200, v10
	v_lshlrev_b32_e32 v0, 2, v10
	s_lshl_b64 s[6:7], s[6:7], 2
	v_ashrrev_i32_e32 v14, 4, v10
	v_ashrrev_i32_e32 v15, 4, v11
	v_and_b32_e32 v12, 60, v0
	s_add_u32 s6, s5, s6
	s_waitcnt vmcnt(0)
	v_add_u32_e32 v4, s9, v14
	v_add_u32_e32 v6, s9, v15
	s_addc_u32 s7, s10, s7
	v_lshlrev_b32_e32 v0, 2, v12
	v_ashrrev_i32_e32 v5, 31, v4
	v_ashrrev_i32_e32 v7, 31, v6
	v_lshl_add_u64 v[2:3], s[6:7], 0, v[0:1]
	v_lshlrev_b64 v[4:5], 12, v[4:5]
	v_lshlrev_b64 v[6:7], 12, v[6:7]
	v_lshl_add_u64 v[4:5], v[2:3], 0, v[4:5]
	v_lshl_add_u64 v[6:7], v[2:3], 0, v[6:7]
	global_load_dwordx4 v[2:5], v[4:5], off
	s_nop 0
	global_load_dwordx4 v[6:9], v[6:7], off
	v_lshlrev_b32_e32 v13, 1, v10
	v_and_b32_e32 v26, 62, v13
	s_movk_i32 s5, 0x104
	v_mul_u32_u24_e32 v13, 0x41, v26
	v_mul_lo_u32 v16, v14, s5
	v_mul_lo_u32 v17, v15, s5
	v_ashrrev_i32_e32 v18, 5, v10
	v_ashrrev_i32_e32 v20, 5, v11
	v_add_u32_e32 v11, 0x400, v10
	v_add_u32_e32 v10, 0x600, v10
	v_add3_u32 v16, s89, v16, v0
	v_add3_u32 v17, s89, v17, v0
	v_lshl_add_u32 v0, v13, 2, s89
	v_ashrrev_i32_e32 v22, 5, v11
	v_ashrrev_i32_e32 v24, 5, v10
	v_lshl_add_u32 v19, v18, 2, v0
	v_lshl_add_u32 v21, v20, 2, v0
	v_lshl_add_u32 v23, v22, 2, v0
	v_lshl_add_u32 v25, v24, 2, v0
	v_lshlrev_b32_e32 v10, 2, v12
	v_lshlrev_b32_e32 v0, 1, v26
	s_mov_b32 s98, 1
	s_mov_b32 s99, 2
	s_sub_i32 s8, s8, s46
	s_branch .LBB0_967

.Ltq6_latch2:
	s_xor_b32 s98, s98, 1
	s_sub_i32 s99, s99, 1
	s_max_i32 s99, s99, 0
	s_andn2_b64 vcc, exec, s[6:7]
	s_mov_b32 s8, s5
	s_cbranch_vccz .LBB0_977
.LBB0_967:
	s_cmp_eq_u32 s99, 2
	s_cbranch_scc0 .Ltq6_real
	s_add_i32 s5, s8, s46
	s_mov_b64 s[6:7], 0
	s_branch .Ltq6_fchk
.Ltq6_real:
	s_waitcnt lgkmcnt(0)
	s_barrier
	s_add_i32 s5, s8, s46
	s_cmpk_gt_i32 s5, 0xaff
	s_cbranch_scc1 .Ltq6_w0
	s_cmp_eq_u32 s99, 1
	s_cbranch_scc1 .Ltq6_w2
	s_waitcnt vmcnt(6)
	s_branch .Ltq6_wd

.Ltq6_wrd:
	s_waitcnt lgkmcnt(0)
	s_barrier
	s_cmpk_gt_i32 s5, 0xaff
	s_cselect_b64 s[6:7], -1, 0
.Ltq6_fchk:
	s_add_i32 s100, s5, s46
	s_cmpk_gt_i32 s100, 0xaff
	s_cbranch_scc1 .Ltq6_nof
	s_cmp_eq_u32 s98, 0
	s_cbranch_scc0 .Ltq6_fB
	s_mul_hi_i32 s9, s100, 0x2e8ba2e9
	s_lshr_b32 s10, s9, 31
	s_ashr_i32 s9, s9, 7
	s_add_i32 s9, s9, s10
	s_mul_i32 s10, s9, 0xfffffd40
	s_add_i32 s10, s100, s10
	s_bfe_u32 s11, s10, 0x4001b
	s_add_i32 s11, s10, s11
	s_sext_i32_i16 s12, s11
	s_and_b32 s11, s11, 0xfff0
	s_sub_i32 s10, s10, s11
	s_lshl_b32 s12, s12, 2
	s_sext_i32_i16 s10, s10
	s_andn2_b32 s12, s12, 63
	s_lshl_b32 s10, s10, 6
	s_mul_hi_i32 s11, s9, 0xb00000
	s_mul_i32 s9, s9, 0xb00000
	s_add_u32 s9, s2, s9
	s_addc_u32 s13, s3, s11
	s_ashr_i32 s11, s10, 31
	s_lshl_b64 s[10:11], s[10:11], 2
	s_add_u32 s10, s9, s10
	v_add_u32_e32 v4, s12, v14
	v_add_u32_e32 v6, s12, v15
	s_addc_u32 s11, s13, s11
	v_mov_b32_e32 v11, v1
	v_ashrrev_i32_e32 v5, 31, v4
	v_ashrrev_i32_e32 v7, 31, v6
	v_lshl_add_u64 v[2:3], s[10:11], 0, v[10:11]
	v_lshlrev_b64 v[4:5], 12, v[4:5]
	v_lshlrev_b64 v[6:7], 12, v[6:7]
	v_lshl_add_u64 v[4:5], v[2:3], 0, v[4:5]
	v_lshl_add_u64 v[6:7], v[2:3], 0, v[6:7]
	global_load_dwordx4 v[2:5], v[4:5], off
	s_nop 0
	global_load_dwordx4 v[6:9], v[6:7], off
	s_branch .Ltq6_nof
.Ltq6_fB:
	s_mul_hi_i32 s9, s100, 0x2e8ba2e9
	s_lshr_b32 s10, s9, 31
	s_ashr_i32 s9, s9, 7
	s_add_i32 s9, s9, s10
	s_mul_i32 s10, s9, 0xfffffd40
	s_add_i32 s10, s100, s10
	s_bfe_u32 s11, s10, 0x4001b
	s_add_i32 s11, s10, s11
	s_sext_i32_i16 s12, s11
	s_and_b32 s11, s11, 0xfff0
	s_sub_i32 s10, s10, s11
	s_lshl_b32 s12, s12, 2
	s_sext_i32_i16 s10, s10
	s_andn2_b32 s12, s12, 63
	s_lshl_b32 s10, s10, 6
	s_mul_hi_i32 s11, s9, 0xb00000
	s_mul_i32 s9, s9, 0xb00000
	s_add_u32 s9, s2, s9
	s_addc_u32 s13, s3, s11
	s_ashr_i32 s11, s10, 31
	s_lshl_b64 s[10:11], s[10:11], 2
	s_add_u32 s10, s9, s10
	v_add_u32_e32 v102, s12, v14
	v_add_u32_e32 v104, s12, v15
	s_addc_u32 s11, s13, s11
	v_mov_b32_e32 v11, v1
	v_ashrrev_i32_e32 v103, 31, v102
	v_ashrrev_i32_e32 v105, 31, v104
	v_lshl_add_u64 v[100:101], s[10:11], 0, v[10:11]
	v_lshlrev_b64 v[102:103], 12, v[102:103]
	v_lshlrev_b64 v[104:105], 12, v[104:105]
	v_lshl_add_u64 v[102:103], v[100:101], 0, v[102:103]
	v_lshl_add_u64 v[104:105], v[100:101], 0, v[104:105]
	global_load_dwordx4 v[100:103], v[102:103], off
	s_nop 0
	global_load_dwordx4 v[104:107], v[104:105], off

.LBB0_977:
	v_mov_b32_e32 v10, v142
	s_mov_b32 s1, s88
	s_waitcnt lgkmcnt(0)
	s_barrier
	s_addk_i32 s1, 0xc8e0
	s_ashr_i32 s2, s1, 31
	s_abs_i32 s1, s1
	v_readlane_b32 s4, v254, 22
	s_mul_hi_u32 s3, s1, s4
	s_mul_i32 s3, s3, s77
	s_sub_i32 s1, s1, s3
	s_sub_i32 s3, s1, s77
	s_cmp_ge_u32 s1, s77
	s_cselect_b32 s1, s3, s1
	s_sub_i32 s3, s1, s77
	s_cmp_ge_u32 s1, s77
	s_cselect_b32 s1, s3, s1
	s_xor_b32 s1, s1, s2
	s_sub_i32 s1, s1, s2
	s_add_i32 s1, s1, s46
	s_ashr_i32 s2, s1, 31
	s_abs_i32 s1, s1
	s_mul_hi_u32 s3, s1, s4
	s_mul_i32 s3, s3, s77
	s_sub_i32 s1, s1, s3
	s_sub_i32 s3, s1, s77
	s_cmp_ge_u32 s1, s77
	s_cselect_b32 s1, s3, s1
	s_sub_i32 s3, s1, s77
	s_cmp_ge_u32 s1, s77
	s_cselect_b32 s1, s3, s1
	s_xor_b32 s1, s1, s2
	s_sub_i32 s8, s1, s2
	s_cmpk_gt_i32 s8, 0x3ff
	s_cbranch_scc1 .LBB0_990
	s_add_u32 s1, s50, 0x6f00000
	s_addc_u32 s4, s51, 0
	s_ashr_i32 s5, s8, 31
	s_lshr_b32 s5, s5, 24
	s_add_i32 s5, s8, s5
	s_ashr_i32 s6, s5, 8
	s_and_b32 s5, s5, 0xff00
	s_sub_i32 s5, s8, s5
	v_readlane_b32 s2, v254, 60
	s_sext_i32_i16 s7, s5
	v_readlane_b32 s3, v254, 61
	s_bfe_u32 s7, s7, 0x4001b
	s_load_dwordx2 s[2:3], s[2:3], 0x120
	s_add_i32 s7, s5, s7
	s_sext_i32_i16 s9, s7
	s_and_b32 s7, s7, 0xfff0
	s_sub_i32 s5, s5, s7
	s_lshl_b32 s9, s9, 2
	s_sext_i32_i16 s5, s5
	s_ashr_i32 s7, s6, 31
	s_andn2_b32 s9, s9, 63
	s_lshl_b32 s10, s5, 6
	s_lshl_b64 s[6:7], s[6:7], 22
	s_waitcnt lgkmcnt(0)
	s_add_u32 s5, s2, s6
	s_addc_u32 s12, s3, s7
	s_ashr_i32 s11, s10, 31
	v_add_u32_e32 v11, 0x200, v10
	v_lshlrev_b32_e32 v0, 2, v10
	s_lshl_b64 s[6:7], s[10:11], 2
	v_ashrrev_i32_e32 v14, 4, v10
	v_ashrrev_i32_e32 v15, 4, v11
	v_and_b32_e32 v12, 60, v0
	s_add_u32 s6, s5, s6
	s_waitcnt vmcnt(0)
	v_add_u32_e32 v4, s9, v14
	v_add_u32_e32 v6, s9, v15
	s_addc_u32 s7, s12, s7
	v_lshlrev_b32_e32 v0, 2, v12
	v_ashrrev_i32_e32 v5, 31, v4
	v_ashrrev_i32_e32 v7, 31, v6
	v_lshl_add_u64 v[2:3], s[6:7], 0, v[0:1]
	v_lshlrev_b64 v[4:5], 12, v[4:5]
	v_lshlrev_b64 v[6:7], 12, v[6:7]
	v_lshl_add_u64 v[4:5], v[2:3], 0, v[4:5]
	v_lshl_add_u64 v[6:7], v[2:3], 0, v[6:7]
	global_load_dwordx4 v[2:5], v[4:5], off
	s_nop 0
	global_load_dwordx4 v[6:9], v[6:7], off
	v_lshlrev_b32_e32 v13, 1, v10
	v_and_b32_e32 v26, 62, v13
	s_movk_i32 s5, 0x104
	v_mul_u32_u24_e32 v13, 0x41, v26
	v_mul_lo_u32 v16, v14, s5
	v_mul_lo_u32 v17, v15, s5
	v_ashrrev_i32_e32 v18, 5, v10
	v_ashrrev_i32_e32 v20, 5, v11
	v_add_u32_e32 v11, 0x400, v10
	v_add_u32_e32 v10, 0x600, v10
	v_add3_u32 v16, s89, v16, v0
	v_add3_u32 v17, s89, v17, v0
	v_lshl_add_u32 v0, v13, 2, s89
	v_ashrrev_i32_e32 v22, 5, v11
	v_ashrrev_i32_e32 v24, 5, v10
	v_lshl_add_u32 v19, v18, 2, v0
	v_lshl_add_u32 v21, v20, 2, v0
	v_lshl_add_u32 v23, v22, 2, v0
	v_lshl_add_u32 v25, v24, 2, v0
	v_lshlrev_b32_e32 v10, 2, v12
	v_lshlrev_b32_e32 v0, 1, v26
	s_mov_b32 s98, 1
	s_mov_b32 s99, 2
	s_sub_i32 s8, s8, s46
	s_branch .LBB0_980

.Ltq7_real:
	s_waitcnt lgkmcnt(0)
	s_barrier
	s_add_i32 s5, s8, s46
	s_cmpk_gt_i32 s5, 0x3ff
	s_cbranch_scc1 .Ltq7_w0
	s_cmp_eq_u32 s99, 1
	s_cbranch_scc1 .Ltq7_w2
	s_waitcnt vmcnt(6)
	s_branch .Ltq7_wd

.Ltq7_wrd:
	s_waitcnt lgkmcnt(0)
	s_barrier
	s_cmpk_gt_i32 s5, 0x3ff
	s_cselect_b64 s[6:7], -1, 0
.Ltq7_fchk:
	s_add_i32 s100, s5, s46
	s_cmpk_gt_i32 s100, 0x3ff
	s_cbranch_scc1 .Ltq7_nof
	s_cmp_eq_u32 s98, 0
	s_cbranch_scc0 .Ltq7_fB
	s_ashr_i32 s9, s100, 31
	s_lshr_b32 s9, s9, 24
	s_add_i32 s9, s100, s9
	s_ashr_i32 s10, s9, 8
	s_and_b32 s9, s9, 0xff00
	s_sub_i32 s9, s100, s9
	s_sext_i32_i16 s11, s9
	s_bfe_u32 s11, s11, 0x4001b
	s_add_i32 s11, s9, s11
	s_sext_i32_i16 s12, s11
	s_and_b32 s11, s11, 0xfff0
	s_sub_i32 s9, s9, s11
	s_lshl_b32 s12, s12, 2
	s_sext_i32_i16 s9, s9
	s_ashr_i32 s11, s10, 31
	s_and_b32 s14, s12, 0xffffffc0
	s_lshl_b32 s12, s9, 6
	s_lshl_b64 s[10:11], s[10:11], 22
	s_add_u32 s9, s2, s10
	s_addc_u32 s15, s3, s11
	s_ashr_i32 s13, s12, 31
	s_lshl_b64 s[10:11], s[12:13], 2
	s_add_u32 s10, s9, s10
	v_add_u32_e32 v4, s14, v14
	v_add_u32_e32 v6, s14, v15
	s_addc_u32 s11, s15, s11
	v_mov_b32_e32 v11, v1
	v_ashrrev_i32_e32 v5, 31, v4
	v_ashrrev_i32_e32 v7, 31, v6
	v_lshl_add_u64 v[2:3], s[10:11], 0, v[10:11]
	v_lshlrev_b64 v[4:5], 12, v[4:5]
	v_lshlrev_b64 v[6:7], 12, v[6:7]
	v_lshl_add_u64 v[4:5], v[2:3], 0, v[4:5]
	v_lshl_add_u64 v[6:7], v[2:3], 0, v[6:7]
	global_load_dwordx4 v[2:5], v[4:5], off
	s_nop 0
	global_load_dwordx4 v[6:9], v[6:7], off
	s_branch .Ltq7_nof
.Ltq7_fB:
	s_ashr_i32 s9, s100, 31
	s_lshr_b32 s9, s9, 24
	s_add_i32 s9, s100, s9
	s_ashr_i32 s10, s9, 8
	s_and_b32 s9, s9, 0xff00
	s_sub_i32 s9, s100, s9
	s_sext_i32_i16 s11, s9
	s_bfe_u32 s11, s11, 0x4001b
	s_add_i32 s11, s9, s11
	s_sext_i32_i16 s12, s11
	s_and_b32 s11, s11, 0xfff0
	s_sub_i32 s9, s9, s11
	s_lshl_b32 s12, s12, 2
	s_sext_i32_i16 s9, s9
	s_ashr_i32 s11, s10, 31
	s_and_b32 s14, s12, 0xffffffc0
	s_lshl_b32 s12, s9, 6
	s_lshl_b64 s[10:11], s[10:11], 22
	s_add_u32 s9, s2, s10
	s_addc_u32 s15, s3, s11
	s_ashr_i32 s13, s12, 31
	s_lshl_b64 s[10:11], s[12:13], 2
	s_add_u32 s10, s9, s10
	v_add_u32_e32 v102, s14, v14
	v_add_u32_e32 v104, s14, v15
	s_addc_u32 s11, s15, s11
	v_mov_b32_e32 v11, v1
	v_ashrrev_i32_e32 v103, 31, v102
	v_ashrrev_i32_e32 v105, 31, v104
	v_lshl_add_u64 v[100:101], s[10:11], 0, v[10:11]
	v_lshlrev_b64 v[102:103], 12, v[102:103]
	v_lshlrev_b64 v[104:105], 12, v[104:105]
	v_lshl_add_u64 v[102:103], v[100:101], 0, v[102:103]
	v_lshl_add_u64 v[104:105], v[100:101], 0, v[104:105]
	global_load_dwordx4 v[100:103], v[102:103], off
	s_nop 0
	global_load_dwordx4 v[104:107], v[104:105], off

.LBB0_990:
	v_mov_b32_e32 v10, v142
	s_mov_b32 s1, s88
	s_waitcnt lgkmcnt(0)
	s_barrier
	s_addk_i32 s1, 0xc4e0
	s_ashr_i32 s2, s1, 31
	s_abs_i32 s1, s1
	v_readlane_b32 s4, v254, 22
	s_mul_hi_u32 s3, s1, s4
	s_mul_i32 s3, s3, s77
	s_sub_i32 s1, s1, s3
	s_sub_i32 s3, s1, s77
	s_cmp_ge_u32 s1, s77
	s_cselect_b32 s1, s3, s1
	s_sub_i32 s3, s1, s77
	s_cmp_ge_u32 s1, s77
	s_cselect_b32 s1, s3, s1
	s_xor_b32 s1, s1, s2
	s_sub_i32 s1, s1, s2
	s_add_i32 s1, s1, s46
	s_ashr_i32 s2, s1, 31
	s_abs_i32 s1, s1
	s_mul_hi_u32 s3, s1, s4
	s_mul_i32 s3, s3, s77
	s_sub_i32 s1, s1, s3
	s_sub_i32 s3, s1, s77
	s_cmp_ge_u32 s1, s77
	s_cselect_b32 s1, s3, s1
	s_sub_i32 s3, s1, s77
	s_cmp_ge_u32 s1, s77
	s_cselect_b32 s1, s3, s1
	s_xor_b32 s1, s1, s2
	s_sub_i32 s8, s1, s2
	s_cmpk_gt_i32 s8, 0xff
	s_cbranch_scc1 .LBB0_1003
	s_add_u32 s1, s50, 0x7700000
	s_addc_u32 s4, s51, 0
	s_ashr_i32 s5, s8, 31
	s_lshr_b32 s5, s5, 26
	s_add_i32 s5, s8, s5
	s_ashr_i32 s6, s5, 6
	s_and_b32 s5, s5, 0xffc0
	s_sub_i32 s5, s8, s5
	v_readlane_b32 s2, v254, 60
	s_bfe_i32 s7, s5, 0x80000
	v_readlane_b32 s3, v254, 61
	s_bfe_u32 s7, s7, 0x4000b
	s_load_dwordx2 s[2:3], s[2:3], 0x118
	s_add_i32 s7, s5, s7
	s_bfe_i32 s9, s7, 0x80000
	s_and_b32 s7, s7, 0xf0
	s_sext_i32_i16 s9, s9
	s_sub_i32 s5, s5, s7
	s_lshl_b32 s9, s9, 2
	s_sext_i32_i8 s5, s5
	s_ashr_i32 s7, s6, 31
	s_andn2_b32 s9, s9, 63
	s_lshl_b32 s10, s5, 6
	s_lshl_b64 s[6:7], s[6:7], 20
	s_waitcnt lgkmcnt(0)
	s_add_u32 s5, s2, s6
	s_addc_u32 s12, s3, s7
	s_ashr_i32 s11, s10, 31
	v_add_u32_e32 v11, 0x200, v10
	v_lshlrev_b32_e32 v0, 2, v10
	s_lshl_b64 s[6:7], s[10:11], 2
	v_ashrrev_i32_e32 v14, 4, v10
	v_ashrrev_i32_e32 v15, 4, v11
	v_and_b32_e32 v12, 60, v0
	s_add_u32 s6, s5, s6
	s_waitcnt vmcnt(0)
	v_add_u32_e32 v4, s9, v14
	v_add_u32_e32 v6, s9, v15
	s_addc_u32 s7, s12, s7
	v_lshlrev_b32_e32 v0, 2, v12
	v_ashrrev_i32_e32 v5, 31, v4
	v_ashrrev_i32_e32 v7, 31, v6
	v_lshl_add_u64 v[2:3], s[6:7], 0, v[0:1]
	v_lshlrev_b64 v[4:5], 12, v[4:5]
	v_lshlrev_b64 v[6:7], 12, v[6:7]
	v_lshl_add_u64 v[4:5], v[2:3], 0, v[4:5]
	v_lshl_add_u64 v[6:7], v[2:3], 0, v[6:7]
	global_load_dwordx4 v[2:5], v[4:5], off
	s_nop 0
	global_load_dwordx4 v[6:9], v[6:7], off
	v_lshlrev_b32_e32 v13, 1, v10
	v_and_b32_e32 v26, 62, v13
	s_movk_i32 s5, 0x104
	v_mul_u32_u24_e32 v13, 0x41, v26
	v_mul_lo_u32 v16, v14, s5
	v_mul_lo_u32 v17, v15, s5
	v_ashrrev_i32_e32 v18, 5, v10
	v_ashrrev_i32_e32 v20, 5, v11
	v_add_u32_e32 v11, 0x400, v10
	v_add_u32_e32 v10, 0x600, v10
	v_add3_u32 v16, s89, v16, v0
	v_add3_u32 v17, s89, v17, v0
	v_lshl_add_u32 v0, v13, 2, s89
	v_ashrrev_i32_e32 v22, 5, v11
	v_ashrrev_i32_e32 v24, 5, v10
	v_lshl_add_u32 v19, v18, 2, v0
	v_lshl_add_u32 v21, v20, 2, v0
	v_lshl_add_u32 v23, v22, 2, v0
	v_lshl_add_u32 v25, v24, 2, v0
	v_lshlrev_b32_e32 v10, 2, v12
	v_lshlrev_b32_e32 v0, 1, v26
	s_mov_b32 s98, 1
	s_mov_b32 s99, 2
	s_sub_i32 s8, s8, s46
	s_branch .LBB0_993

.Ltq8_real:
	s_waitcnt lgkmcnt(0)
	s_barrier
	s_add_i32 s5, s8, s46
	s_cmpk_gt_i32 s5, 0xff
	s_cbranch_scc1 .Ltq8_w0
	s_cmp_eq_u32 s99, 1
	s_cbranch_scc1 .Ltq8_w2
	s_waitcnt vmcnt(6)
	s_branch .Ltq8_wd

.Ltq8_wrd:
	s_waitcnt lgkmcnt(0)
	s_barrier
	s_cmpk_gt_i32 s5, 0xff
	s_cselect_b64 s[6:7], -1, 0
.Ltq8_fchk:
	s_add_i32 s100, s5, s46
	s_cmpk_gt_i32 s100, 0xff
	s_cbranch_scc1 .Ltq8_nof
	s_cmp_eq_u32 s98, 0
	s_cbranch_scc0 .Ltq8_fB
	s_ashr_i32 s9, s100, 31
	s_lshr_b32 s9, s9, 26
	s_add_i32 s9, s100, s9
	s_ashr_i32 s10, s9, 6
	s_and_b32 s9, s9, 0xffc0
	s_sub_i32 s9, s100, s9
	s_bfe_i32 s11, s9, 0x80000
	s_bfe_u32 s11, s11, 0x4000b
	s_add_i32 s11, s9, s11
	s_bfe_i32 s12, s11, 0x80000
	s_and_b32 s11, s11, 0xf0
	s_sext_i32_i16 s12, s12
	s_sub_i32 s9, s9, s11
	s_lshl_b32 s12, s12, 2
	s_sext_i32_i8 s9, s9
	s_ashr_i32 s11, s10, 31
	s_and_b32 s14, s12, 0xffffffc0
	s_lshl_b32 s12, s9, 6
	s_lshl_b64 s[10:11], s[10:11], 20
	s_add_u32 s9, s2, s10
	s_addc_u32 s15, s3, s11
	s_ashr_i32 s13, s12, 31
	s_lshl_b64 s[10:11], s[12:13], 2
	s_add_u32 s10, s9, s10
	v_add_u32_e32 v4, s14, v14
	v_add_u32_e32 v6, s14, v15
	s_addc_u32 s11, s15, s11
	v_mov_b32_e32 v11, v1
	v_ashrrev_i32_e32 v5, 31, v4
	v_ashrrev_i32_e32 v7, 31, v6
	v_lshl_add_u64 v[2:3], s[10:11], 0, v[10:11]
	v_lshlrev_b64 v[4:5], 12, v[4:5]
	v_lshlrev_b64 v[6:7], 12, v[6:7]
	v_lshl_add_u64 v[4:5], v[2:3], 0, v[4:5]
	v_lshl_add_u64 v[6:7], v[2:3], 0, v[6:7]
	global_load_dwordx4 v[2:5], v[4:5], off
	s_nop 0
	global_load_dwordx4 v[6:9], v[6:7], off
	s_branch .Ltq8_nof
.Ltq8_fB:
	s_ashr_i32 s9, s100, 31
	s_lshr_b32 s9, s9, 26
	s_add_i32 s9, s100, s9
	s_ashr_i32 s10, s9, 6
	s_and_b32 s9, s9, 0xffc0
	s_sub_i32 s9, s100, s9
	s_bfe_i32 s11, s9, 0x80000
	s_bfe_u32 s11, s11, 0x4000b
	s_add_i32 s11, s9, s11
	s_bfe_i32 s12, s11, 0x80000
	s_and_b32 s11, s11, 0xf0
	s_sext_i32_i16 s12, s12
	s_sub_i32 s9, s9, s11
	s_lshl_b32 s12, s12, 2
	s_sext_i32_i8 s9, s9
	s_ashr_i32 s11, s10, 31
	s_and_b32 s14, s12, 0xffffffc0
	s_lshl_b32 s12, s9, 6
	s_lshl_b64 s[10:11], s[10:11], 20
	s_add_u32 s9, s2, s10
	s_addc_u32 s15, s3, s11
	s_ashr_i32 s13, s12, 31
	s_lshl_b64 s[10:11], s[12:13], 2
	s_add_u32 s10, s9, s10
	v_add_u32_e32 v102, s14, v14
	v_add_u32_e32 v104, s14, v15
	s_addc_u32 s11, s15, s11
	v_mov_b32_e32 v11, v1
	v_ashrrev_i32_e32 v103, 31, v102
	v_ashrrev_i32_e32 v105, 31, v104
	v_lshl_add_u64 v[100:101], s[10:11], 0, v[10:11]
	v_lshlrev_b64 v[102:103], 12, v[102:103]
	v_lshlrev_b64 v[104:105], 12, v[104:105]
	v_lshl_add_u64 v[102:103], v[100:101], 0, v[102:103]
	v_lshl_add_u64 v[104:105], v[100:101], 0, v[104:105]
	global_load_dwordx4 v[100:103], v[102:103], off
	s_nop 0
	global_load_dwordx4 v[104:107], v[104:105], off
